# scale-table lane table and repeated-row skip plus the top-16 small-item shortcut together, padded so the GEMM loops keep their addresses modulo 256
# speedup vs baseline: 1.0011x; 1.0003x over previous
.LBB0_244:
	v_mov_b32_e32 v0, v222
	s_waitcnt lgkmcnt(0)
	s_barrier
	s_nop 0
	v_lshlrev_b32_e32 v0, 2, v0
	v_xor_b32_e32 v0, 0x80, v0
	ds_bpermute_b32 v0, v0, v187
	s_waitcnt lgkmcnt(0)
	v_add_f32_e32 v0, v187, v0
	v_div_scale_f32 v66, s[0:1], v0, v0, 1.0
	v_rcp_f32_e32 v67, v66
	v_div_scale_f32 v68, vcc, 1.0, v0, 1.0
	v_fma_f32 v69, -v66, v67, 1.0
	v_fmac_f32_e32 v67, v69, v67
	v_mul_f32_e32 v69, v68, v67
	v_fma_f32 v70, -v66, v69, v68
	v_fmac_f32_e32 v69, v70, v67
	v_fma_f32 v66, -v66, v69, v68
	v_div_fmas_f32 v66, v66, v67, v69
	v_div_fixup_f32 v66, v66, v0, 1.0
	v_cmp_lt_f32_e32 vcc, 0, v0
	s_nop 1
	v_cndmask_b32_e32 v140, 0, v66, vcc
	v_mul_f32_e32 v0, v50, v140
	v_mul_f32_e32 v226, v51, v140
	v_mul_f32_e32 v227, v52, v140
	v_mov_b32_dpp v0, v0 row_ror:8 row_mask:0xf bank_mask:0xf
	v_mov_b32_dpp v226, v226 row_ror:8 row_mask:0xf bank_mask:0xf
	v_mov_b32_dpp v227, v227 row_ror:8 row_mask:0xf bank_mask:0xf
	v_fmac_f32_e32 v0, v50, v140
	v_fmac_f32_e32 v226, v51, v140
	v_fmac_f32_e32 v227, v52, v140
	v_mov_b32_e32 v50, v0
	v_mov_b32_e32 v51, v226
	v_mov_b32_e32 v52, v227
	v_permlane16_swap_b32_e32 v50, v0
	v_permlane16_swap_b32_e32 v51, v226
	v_permlane16_swap_b32_e32 v52, v227
	v_add_f32_e32 v0, v50, v0
	v_add_f32_e32 v226, v51, v226
	v_add_f32_e32 v227, v52, v227
	s_and_saveexec_b64 s[0:1], s[4:5]
	ds_write_b32 v177, v0 offset:36864
	ds_write_b32 v177, v226 offset:36868
	ds_write_b32 v177, v227 offset:36872
	s_or_b64 exec, exec, s[0:1]
	v_mul_f32_e32 v0, v53, v140
	v_mul_f32_e32 v226, v54, v140
	v_mul_f32_e32 v227, v55, v140
	v_mov_b32_dpp v0, v0 row_ror:8 row_mask:0xf bank_mask:0xf
	v_mov_b32_dpp v226, v226 row_ror:8 row_mask:0xf bank_mask:0xf
	v_mov_b32_dpp v227, v227 row_ror:8 row_mask:0xf bank_mask:0xf
	v_fmac_f32_e32 v0, v53, v140
	v_fmac_f32_e32 v226, v54, v140
	v_fmac_f32_e32 v227, v55, v140
	v_mov_b32_e32 v53, v0
	v_mov_b32_e32 v54, v226
	v_mov_b32_e32 v55, v227
	v_permlane16_swap_b32_e32 v53, v0
	v_permlane16_swap_b32_e32 v54, v226
	v_permlane16_swap_b32_e32 v55, v227
	v_add_f32_e32 v0, v53, v0
	v_add_f32_e32 v226, v54, v226
	v_add_f32_e32 v227, v55, v227
	s_and_saveexec_b64 s[0:1], s[4:5]
	ds_write_b32 v177, v0 offset:36876
	ds_write_b32 v177, v226 offset:36896
	ds_write_b32 v177, v227 offset:36900
	s_or_b64 exec, exec, s[0:1]
	v_mul_f32_e32 v0, v56, v140
	v_mul_f32_e32 v226, v57, v140
	v_mul_f32_e32 v227, v58, v140
	v_mov_b32_dpp v0, v0 row_ror:8 row_mask:0xf bank_mask:0xf
	v_mov_b32_dpp v226, v226 row_ror:8 row_mask:0xf bank_mask:0xf
	v_mov_b32_dpp v227, v227 row_ror:8 row_mask:0xf bank_mask:0xf
	v_fmac_f32_e32 v0, v56, v140
	v_fmac_f32_e32 v226, v57, v140
	v_fmac_f32_e32 v227, v58, v140
	v_mov_b32_e32 v56, v0
	v_mov_b32_e32 v57, v226
	v_mov_b32_e32 v58, v227
	v_permlane16_swap_b32_e32 v56, v0
	v_permlane16_swap_b32_e32 v57, v226
	v_permlane16_swap_b32_e32 v58, v227
	v_add_f32_e32 v0, v56, v0
	v_add_f32_e32 v226, v57, v226
	v_add_f32_e32 v227, v58, v227
	s_and_saveexec_b64 s[0:1], s[4:5]
	ds_write_b32 v177, v0 offset:36904
	ds_write_b32 v177, v226 offset:36908
	ds_write_b32 v177, v227 offset:36928
	s_or_b64 exec, exec, s[0:1]
	v_mul_f32_e32 v0, v59, v140
	v_mul_f32_e32 v226, v60, v140
	v_mul_f32_e32 v227, v61, v140
	v_mov_b32_dpp v0, v0 row_ror:8 row_mask:0xf bank_mask:0xf
	v_mov_b32_dpp v226, v226 row_ror:8 row_mask:0xf bank_mask:0xf
	v_mov_b32_dpp v227, v227 row_ror:8 row_mask:0xf bank_mask:0xf
	v_fmac_f32_e32 v0, v59, v140
	v_fmac_f32_e32 v226, v60, v140
	v_fmac_f32_e32 v227, v61, v140
	v_mov_b32_e32 v59, v0
	v_mov_b32_e32 v60, v226
	v_mov_b32_e32 v61, v227
	v_permlane16_swap_b32_e32 v59, v0
	v_permlane16_swap_b32_e32 v60, v226
	v_permlane16_swap_b32_e32 v61, v227
	v_add_f32_e32 v0, v59, v0
	v_add_f32_e32 v226, v60, v226
	v_add_f32_e32 v227, v61, v227
	s_and_saveexec_b64 s[0:1], s[4:5]
	ds_write_b32 v177, v0 offset:36932
	ds_write_b32 v177, v226 offset:36936
	ds_write_b32 v177, v227 offset:36940
	s_or_b64 exec, exec, s[0:1]
	v_mul_f32_e32 v0, v62, v140
	v_mul_f32_e32 v226, v63, v140
	v_mul_f32_e32 v227, v64, v140
	v_mov_b32_dpp v0, v0 row_ror:8 row_mask:0xf bank_mask:0xf
	v_mov_b32_dpp v226, v226 row_ror:8 row_mask:0xf bank_mask:0xf
	v_mov_b32_dpp v227, v227 row_ror:8 row_mask:0xf bank_mask:0xf
	v_fmac_f32_e32 v0, v62, v140
	v_fmac_f32_e32 v226, v63, v140
	v_fmac_f32_e32 v227, v64, v140
	v_mov_b32_e32 v62, v0
	v_mov_b32_e32 v63, v226
	v_mov_b32_e32 v64, v227
	v_permlane16_swap_b32_e32 v62, v0
	v_permlane16_swap_b32_e32 v63, v226
	v_permlane16_swap_b32_e32 v64, v227
	v_add_f32_e32 v0, v62, v0
	v_add_f32_e32 v226, v63, v226
	v_add_f32_e32 v227, v64, v227
	s_and_saveexec_b64 s[0:1], s[4:5]
	ds_write_b32 v177, v0 offset:36960
	ds_write_b32 v177, v226 offset:36964
	ds_write_b32 v177, v227 offset:36968
	s_or_b64 exec, exec, s[0:1]
	v_mul_f32_e32 v0, v65, v140
	v_mul_f32_e32 v226, v34, v140
	v_mul_f32_e32 v227, v35, v140
	v_mov_b32_dpp v0, v0 row_ror:8 row_mask:0xf bank_mask:0xf
	v_mov_b32_dpp v226, v226 row_ror:8 row_mask:0xf bank_mask:0xf
	v_mov_b32_dpp v227, v227 row_ror:8 row_mask:0xf bank_mask:0xf
	v_fmac_f32_e32 v0, v65, v140
	v_fmac_f32_e32 v226, v34, v140
	v_fmac_f32_e32 v227, v35, v140
	v_mov_b32_e32 v65, v0
	v_mov_b32_e32 v34, v226
	v_mov_b32_e32 v35, v227
	v_permlane16_swap_b32_e32 v65, v0
	v_permlane16_swap_b32_e32 v34, v226
	v_permlane16_swap_b32_e32 v35, v227
	v_add_f32_e32 v0, v65, v0
	v_add_f32_e32 v226, v34, v226
	v_add_f32_e32 v227, v35, v227
	s_and_saveexec_b64 s[0:1], s[4:5]
	ds_write_b32 v177, v0 offset:36972
	ds_write_b32 v177, v226 offset:36992
	ds_write_b32 v177, v227 offset:36996
	s_or_b64 exec, exec, s[0:1]
	v_mul_f32_e32 v0, v36, v140
	v_mul_f32_e32 v226, v37, v140
	v_mul_f32_e32 v227, v38, v140
	v_mov_b32_dpp v0, v0 row_ror:8 row_mask:0xf bank_mask:0xf
	v_mov_b32_dpp v226, v226 row_ror:8 row_mask:0xf bank_mask:0xf
	v_mov_b32_dpp v227, v227 row_ror:8 row_mask:0xf bank_mask:0xf
	v_fmac_f32_e32 v0, v36, v140
	v_fmac_f32_e32 v226, v37, v140
	v_fmac_f32_e32 v227, v38, v140
	v_mov_b32_e32 v36, v0
	v_mov_b32_e32 v37, v226
	v_mov_b32_e32 v38, v227
	v_permlane16_swap_b32_e32 v36, v0
	v_permlane16_swap_b32_e32 v37, v226
	v_permlane16_swap_b32_e32 v38, v227
	v_add_f32_e32 v0, v36, v0
	v_add_f32_e32 v226, v37, v226
	v_add_f32_e32 v227, v38, v227
	s_and_saveexec_b64 s[0:1], s[4:5]
	ds_write_b32 v177, v0 offset:37000
	ds_write_b32 v177, v226 offset:37004
	ds_write_b32 v177, v227 offset:37024
	s_or_b64 exec, exec, s[0:1]
	v_mul_f32_e32 v0, v39, v140
	v_mul_f32_e32 v226, v40, v140
	v_mul_f32_e32 v227, v41, v140
	v_mov_b32_dpp v0, v0 row_ror:8 row_mask:0xf bank_mask:0xf
	v_mov_b32_dpp v226, v226 row_ror:8 row_mask:0xf bank_mask:0xf
	v_mov_b32_dpp v227, v227 row_ror:8 row_mask:0xf bank_mask:0xf
	v_fmac_f32_e32 v0, v39, v140
	v_fmac_f32_e32 v226, v40, v140
	v_fmac_f32_e32 v227, v41, v140
	v_mov_b32_e32 v39, v0
	v_mov_b32_e32 v40, v226
	v_mov_b32_e32 v41, v227
	v_permlane16_swap_b32_e32 v39, v0
	v_permlane16_swap_b32_e32 v40, v226
	v_permlane16_swap_b32_e32 v41, v227
	v_add_f32_e32 v0, v39, v0
	v_add_f32_e32 v226, v40, v226
	v_add_f32_e32 v227, v41, v227
	s_and_saveexec_b64 s[0:1], s[4:5]
	ds_write_b32 v177, v0 offset:37028
	ds_write_b32 v177, v226 offset:37032
	ds_write_b32 v177, v227 offset:37036
	s_or_b64 exec, exec, s[0:1]
	v_mul_f32_e32 v0, v42, v140
	v_mul_f32_e32 v226, v43, v140
	v_mul_f32_e32 v227, v44, v140
	v_mov_b32_dpp v0, v0 row_ror:8 row_mask:0xf bank_mask:0xf
	v_mov_b32_dpp v226, v226 row_ror:8 row_mask:0xf bank_mask:0xf
	v_mov_b32_dpp v227, v227 row_ror:8 row_mask:0xf bank_mask:0xf
	v_fmac_f32_e32 v0, v42, v140
	v_fmac_f32_e32 v226, v43, v140
	v_fmac_f32_e32 v227, v44, v140
	v_mov_b32_e32 v42, v0
	v_mov_b32_e32 v43, v226
	v_mov_b32_e32 v44, v227
	v_permlane16_swap_b32_e32 v42, v0
	v_permlane16_swap_b32_e32 v43, v226
	v_permlane16_swap_b32_e32 v44, v227
	v_add_f32_e32 v0, v42, v0
	v_add_f32_e32 v226, v43, v226
	v_add_f32_e32 v227, v44, v227
	s_and_saveexec_b64 s[0:1], s[4:5]
	ds_write_b32 v177, v0 offset:37056
	ds_write_b32 v177, v226 offset:37060
	ds_write_b32 v177, v227 offset:37064
	s_or_b64 exec, exec, s[0:1]
	v_mul_f32_e32 v0, v45, v140
	v_mul_f32_e32 v226, v46, v140
	v_mul_f32_e32 v227, v47, v140
	v_mov_b32_dpp v0, v0 row_ror:8 row_mask:0xf bank_mask:0xf
	v_mov_b32_dpp v226, v226 row_ror:8 row_mask:0xf bank_mask:0xf
	v_mov_b32_dpp v227, v227 row_ror:8 row_mask:0xf bank_mask:0xf
	v_fmac_f32_e32 v0, v45, v140
	v_fmac_f32_e32 v226, v46, v140
	v_fmac_f32_e32 v227, v47, v140
	v_mov_b32_e32 v45, v0
	v_mov_b32_e32 v46, v226
	v_mov_b32_e32 v47, v227
	v_permlane16_swap_b32_e32 v45, v0
	v_permlane16_swap_b32_e32 v46, v226
	v_permlane16_swap_b32_e32 v47, v227
	v_add_f32_e32 v0, v45, v0
	v_add_f32_e32 v226, v46, v226
	v_add_f32_e32 v227, v47, v227
	s_and_saveexec_b64 s[0:1], s[4:5]
	ds_write_b32 v177, v0 offset:37068
	ds_write_b32 v177, v226 offset:37088
	ds_write_b32 v177, v227 offset:37092
	s_or_b64 exec, exec, s[0:1]
	v_mul_f32_e32 v0, v48, v140
	v_mul_f32_e32 v226, v49, v140
	s_nop 0
	v_mov_b32_dpp v0, v0 row_ror:8 row_mask:0xf bank_mask:0xf
	v_mov_b32_dpp v226, v226 row_ror:8 row_mask:0xf bank_mask:0xf
	v_fmac_f32_e32 v0, v48, v140
	v_fmac_f32_e32 v226, v49, v140
	v_mov_b32_e32 v48, v0
	v_mov_b32_e32 v49, v226
	s_nop 0
	v_permlane16_swap_b32_e32 v48, v0
	v_permlane16_swap_b32_e32 v49, v226
	v_add_f32_e32 v0, v48, v0
	v_add_f32_e32 v226, v49, v226
	s_and_saveexec_b64 s[0:1], s[4:5]
	ds_write_b32 v177, v0 offset:37096
	ds_write_b32 v177, v226 offset:37100
	s_or_b64 exec, exec, s[0:1]
	s_waitcnt lgkmcnt(0)
	v_cmp_eq_u32_e32 vcc, s67, v168
	s_or_b64 s[0:1], s[6:7], vcc
	v_cmp_eq_u32_e32 vcc, s67, v207
	s_or_b64 vcc, s[0:1], vcc
	v_cmp_lt_i32_e64 s[0:1], s67, v168
	s_cmp_lt_u32 s67, 16
	s_cbranch_scc0 .Ltopk_full
	s_not_b64 s[20:21], s[0:1]
	s_mov_b64 s[86:87], s[20:21]
	s_mov_b64 s[24:25], s[20:21]
	s_mov_b64 s[26:27], s[20:21]
	s_mov_b64 s[28:29], s[20:21]
	s_mov_b64 s[30:31], s[20:21]
	s_mov_b64 s[10:11], s[20:21]
	s_mov_b64 s[8:9], s[20:21]
	s_and_saveexec_b64 s[12:13], s[6:7]
	v_mov_b32_e32 v0, s70
	v_mov_b64_e32 v[34:35], s[20:21]
	ds_write_b64 v0, v[34:35] offset:53248
	ds_write_b64 v0, v[34:35] offset:53256
	ds_write_b64 v0, v[34:35] offset:53264
	ds_write_b64 v0, v[34:35] offset:53272
	ds_write_b64 v0, v[34:35] offset:53280
	ds_write_b64 v0, v[34:35] offset:53288
	ds_write_b64 v0, v[34:35] offset:53296
	ds_write_b64 v0, v[34:35] offset:53304
	s_or_b64 exec, exec, s[12:13]
	s_nop 0
	s_nop 0
	s_nop 0
	s_nop 0
	s_nop 0
	s_nop 0
	s_nop 0
	s_nop 0
	s_nop 0
	s_nop 0
	s_nop 0
	s_nop 0
	s_nop 0
	s_nop 0
	s_nop 0
	s_nop 0
	s_nop 0
	s_nop 0
	s_nop 0
	s_nop 0
	s_nop 0
	s_nop 0
	s_nop 0
	s_nop 0
	s_nop 0
	s_nop 0
	s_nop 0
	s_nop 0
	s_nop 0
	s_nop 0
	s_nop 0
	s_nop 0
	s_nop 0
	s_branch .Ltopk_end
